# SwiGLU epilogue: address/convert instructions hoisted out of the per-value chains so 31 of 32 chain pairs interleave
# baseline (speedup 1.0000x reference)
; __device__ __forceinline__ unsigned cvt_pk_bf16(float lo, float hi) { unsigned r; asm volatile("v_cvt_pk_bf16_f32 %0, %1, %2" : "=v"(r) : "v"(lo), "v"(hi)); return r; }
; __device__ __forceinline__ float sigmoid_f(float x) { return __builtin_amdgcn_rcpf(1.0f + __builtin_amdgcn_exp2f(-1.4426950408889634f * x)); }
;     __device__ __forceinline__ void operator()(const f32x4 (&acc)[2][2][4][2], const Unit& u, int wr, int wc, int fr, int fq) const {
;         const int row0 = u.pm * BM + wr * 64 + fr, col0 = u.pn * HALF + wc * 32 + 8 * fq;
; #pragma unroll
;         for (int ai = 0; ai < 2; ++ai)
; #pragma unroll
;             for (int m = 0; m < 4; ++m) {
;                 bf16_t* rowp = O + (size_t)(row0 + ai * HALF + m * 16) * ldc + col0;
;                 float v[8];
; #pragma unroll
;                 for (int n = 0; n < 2; ++n)
; #pragma unroll
;                     for (int e = 0; e < 4; ++e) { const float g = acc[ai][0][m][n][e], up = acc[ai][1][m][n][e]; v[4 * n + e] = g * sigmoid_f(g) * up; }
;                 u32x4 w; w.x = cvt_pk_bf16(v[0], v[1]); w.y = cvt_pk_bf16(v[2], v[3]); w.z = cvt_pk_bf16(v[4], v[5]); w.w = cvt_pk_bf16(v[6], v[7]);
;                 *(u32x4*)rowp = w;
;             }
.LBB0_511:
	v_lshl_or_b32 v148, s3, 7, v144
	v_lshl_add_u32 v146, s34, 8, v142
	v_ashrrev_i32_e32 v149, 31, v148
	v_mov_b64_e32 v[140:141], s[78:79]
	v_mad_i64_i32 v[150:151], s[18:19], v146, s89, v[140:141]
	v_mul_f32_e32 v147, 0xbfb8aa3b, v126
	v_exp_f32_e32 v147, v147
	s_nop 0
	v_add_f32_e32 v147, 1.0, v147
	v_rcp_f32_e32 v147, v147
	s_nop 0
	v_mul_f32_e32 v126, v126, v147
	v_mul_f32_e32 v122, v126, v122
	s_mov_b64 s[34:35], -1
	s_andn2_b64 vcc, exec, s[6:7]
	v_mul_f32_e32 v126, 0xbfb8aa3b, v127
	v_mul_f32_e32 v250, 0xbfb8aa3b, v128
	v_exp_f32_e32 v126, v126
	v_exp_f32_e32 v250, v250
	v_add_f32_e32 v126, 1.0, v126
	v_add_f32_e32 v250, 1.0, v250
	v_rcp_f32_e32 v126, v126
	v_rcp_f32_e32 v250, v250
	v_mul_f32_e32 v126, v127, v126
	v_mul_f32_e32 v250, v128, v250
	v_mul_f32_e32 v123, v126, v123
	v_mul_f32_e32 v124, v250, v124
	v_mul_f32_e32 v126, 0xbfb8aa3b, v129
	v_mul_f32_e32 v250, 0xbfb8aa3b, v118
	v_exp_f32_e32 v126, v126
	v_exp_f32_e32 v250, v250
	v_add_f32_e32 v126, 1.0, v126
	v_add_f32_e32 v250, 1.0, v250
	v_rcp_f32_e32 v126, v126
	v_rcp_f32_e32 v250, v250
	v_mul_f32_e32 v126, v129, v126
	v_mul_f32_e32 v250, v118, v250
	v_mul_f32_e32 v125, v126, v125
	v_mul_f32_e32 v118, v250, v114
	v_mul_f32_e32 v114, 0xbfb8aa3b, v119
	v_mul_f32_e32 v250, 0xbfb8aa3b, v120
	v_exp_f32_e32 v114, v114
	v_exp_f32_e32 v250, v250
	v_add_f32_e32 v114, 1.0, v114
	v_add_f32_e32 v250, 1.0, v250
	v_rcp_f32_e32 v114, v114
	v_rcp_f32_e32 v250, v250
	v_mul_f32_e32 v114, v119, v114
	v_mul_f32_e32 v250, v120, v250
	v_mul_f32_e32 v119, v114, v115
	v_mul_f32_e32 v126, v250, v116
	v_cvt_pk_bf16_f32 v116, v122, v123
	v_mul_f32_e32 v114, 0xbfb8aa3b, v121
	v_exp_f32_e32 v114, v114
	s_nop 0
	v_add_f32_e32 v114, 1.0, v114
	v_rcp_f32_e32 v114, v114
	s_nop 0
	v_mul_f32_e32 v114, v121, v114
	v_mul_f32_e32 v127, v114, v117
	v_lshlrev_b64 v[114:115], 1, v[148:149]
	v_lshl_add_u64 v[120:121], v[150:151], 0, v[114:115]
	v_cvt_pk_bf16_f32 v117, v124, v125
	v_cvt_pk_bf16_f32 v118, v118, v119
	v_cvt_pk_bf16_f32 v119, v126, v127
	global_store_dwordx4 v[120:121], v[116:119], off
	s_nop 1
	v_or_b32_e32 v116, 16, v146
	v_mad_i64_i32 v[116:117], s[18:19], v116, s89, v[140:141]
	v_mul_f32_e32 v118, 0xbfb8aa3b, v110
	v_mul_f32_e32 v250, 0xbfb8aa3b, v111
	v_exp_f32_e32 v118, v118
	v_exp_f32_e32 v250, v250
	v_add_f32_e32 v118, 1.0, v118
	v_add_f32_e32 v250, 1.0, v250
	v_rcp_f32_e32 v118, v118
	v_rcp_f32_e32 v250, v250
	v_mul_f32_e32 v110, v110, v118
	v_mul_f32_e32 v250, v111, v250
	v_mul_f32_e32 v106, v110, v106
	v_mul_f32_e32 v107, v250, v107
	v_mul_f32_e32 v110, 0xbfb8aa3b, v112
	v_mul_f32_e32 v250, 0xbfb8aa3b, v113
	v_exp_f32_e32 v110, v110
	v_exp_f32_e32 v250, v250
	v_add_f32_e32 v110, 1.0, v110
	v_add_f32_e32 v250, 1.0, v250
	v_rcp_f32_e32 v110, v110
	v_rcp_f32_e32 v250, v250
	v_mul_f32_e32 v110, v112, v110
	v_mul_f32_e32 v250, v113, v250
	v_mul_f32_e32 v108, v110, v108
	v_mul_f32_e32 v109, v250, v109
	v_mul_f32_e32 v110, 0xbfb8aa3b, v102
	v_mul_f32_e32 v250, 0xbfb8aa3b, v103
	v_exp_f32_e32 v110, v110
	v_exp_f32_e32 v250, v250
	v_add_f32_e32 v110, 1.0, v110
	v_add_f32_e32 v250, 1.0, v250
	v_rcp_f32_e32 v110, v110
	v_rcp_f32_e32 v250, v250
	v_mul_f32_e32 v102, v102, v110
	v_mul_f32_e32 v250, v103, v250
	v_mul_f32_e32 v110, v102, v98
	v_mul_f32_e32 v111, v250, v99
	v_lshl_add_u64 v[102:103], v[116:117], 0, v[114:115]
	v_mul_f32_e32 v98, 0xbfb8aa3b, v104
	v_mul_f32_e32 v250, 0xbfb8aa3b, v105
	v_exp_f32_e32 v98, v98
	v_exp_f32_e32 v250, v250
	v_add_f32_e32 v98, 1.0, v98
	v_add_f32_e32 v250, 1.0, v250
	v_rcp_f32_e32 v98, v98
	v_rcp_f32_e32 v250, v250
	v_mul_f32_e32 v98, v104, v98
	v_mul_f32_e32 v250, v105, v250
	v_mul_f32_e32 v104, v98, v100
	v_mul_f32_e32 v101, v250, v101
	v_cvt_pk_bf16_f32 v98, v106, v107
	v_cvt_pk_bf16_f32 v99, v108, v109
	v_cvt_pk_bf16_f32 v100, v110, v111
	v_cvt_pk_bf16_f32 v101, v104, v101
	global_store_dwordx4 v[102:103], v[98:101], off
	s_nop 1
	v_or_b32_e32 v98, 32, v146
	v_mad_i64_i32 v[98:99], s[18:19], v98, s89, v[140:141]
	v_mul_f32_e32 v100, 0xbfb8aa3b, v94
	v_mul_f32_e32 v250, 0xbfb8aa3b, v95
	v_exp_f32_e32 v100, v100
	v_exp_f32_e32 v250, v250
	v_add_f32_e32 v100, 1.0, v100
	v_add_f32_e32 v250, 1.0, v250
	v_rcp_f32_e32 v100, v100
	v_rcp_f32_e32 v250, v250
	v_mul_f32_e32 v94, v94, v100
	v_mul_f32_e32 v250, v95, v250
	v_mul_f32_e32 v90, v94, v90
	v_mul_f32_e32 v91, v250, v91
	v_mul_f32_e32 v94, 0xbfb8aa3b, v96
	v_mul_f32_e32 v250, 0xbfb8aa3b, v97
	v_exp_f32_e32 v94, v94
	v_exp_f32_e32 v250, v250
	v_add_f32_e32 v94, 1.0, v94
	v_add_f32_e32 v250, 1.0, v250
	v_rcp_f32_e32 v94, v94
	v_rcp_f32_e32 v250, v250
	v_mul_f32_e32 v94, v96, v94
	v_mul_f32_e32 v250, v97, v250
	v_mul_f32_e32 v92, v94, v92
	v_mul_f32_e32 v93, v250, v93
	v_mul_f32_e32 v94, 0xbfb8aa3b, v86
	v_mul_f32_e32 v250, 0xbfb8aa3b, v87
	v_exp_f32_e32 v94, v94
	v_exp_f32_e32 v250, v250
	v_add_f32_e32 v94, 1.0, v94
	v_add_f32_e32 v250, 1.0, v250
	v_rcp_f32_e32 v94, v94
	v_rcp_f32_e32 v250, v250
	v_mul_f32_e32 v86, v86, v94
	v_mul_f32_e32 v250, v87, v250
	v_mul_f32_e32 v94, v86, v82
	v_mul_f32_e32 v95, v250, v83
	v_lshl_add_u64 v[86:87], v[98:99], 0, v[114:115]
	v_mul_f32_e32 v82, 0xbfb8aa3b, v88
	v_mul_f32_e32 v250, 0xbfb8aa3b, v89
	v_exp_f32_e32 v82, v82
	v_exp_f32_e32 v250, v250
	v_add_f32_e32 v82, 1.0, v82
	v_add_f32_e32 v250, 1.0, v250
	v_rcp_f32_e32 v82, v82
	v_rcp_f32_e32 v250, v250
	v_mul_f32_e32 v82, v88, v82
	v_mul_f32_e32 v250, v89, v250
	v_mul_f32_e32 v88, v82, v84
	v_mul_f32_e32 v85, v250, v85
	v_cvt_pk_bf16_f32 v82, v90, v91
	v_cvt_pk_bf16_f32 v83, v92, v93
	v_cvt_pk_bf16_f32 v84, v94, v95
	v_cvt_pk_bf16_f32 v85, v88, v85
	global_store_dwordx4 v[86:87], v[82:85], off
	s_nop 1
	v_or_b32_e32 v82, 48, v146
; __device__ __forceinline__ unsigned cvt_pk_bf16(float lo, float hi) { unsigned r; asm volatile("v_cvt_pk_bf16_f32 %0, %1, %2" : "=v"(r) : "v"(lo), "v"(hi)); return r; }
; __device__ __forceinline__ float sigmoid_f(float x) { return __builtin_amdgcn_rcpf(1.0f + __builtin_amdgcn_exp2f(-1.4426950408889634f * x)); }
;     __device__ __forceinline__ void operator()(const f32x4 (&acc)[2][2][4][2], const Unit& u, int wr, int wc, int fr, int fq) const {
;         const int row0 = u.pm * BM + wr * 64 + fr, col0 = u.pn * HALF + wc * 32 + 8 * fq;
; #pragma unroll
;         for (int ai = 0; ai < 2; ++ai)
; #pragma unroll
;             for (int m = 0; m < 4; ++m) {
;                 bf16_t* rowp = O + (size_t)(row0 + ai * HALF + m * 16) * ldc + col0;
;                 float v[8];
; #pragma unroll
;                 for (int n = 0; n < 2; ++n)
; #pragma unroll
;                     for (int e = 0; e < 4; ++e) { const float g = acc[ai][0][m][n][e], up = acc[ai][1][m][n][e]; v[4 * n + e] = g * sigmoid_f(g) * up; }
;                 u32x4 w; w.x = cvt_pk_bf16(v[0], v[1]); w.y = cvt_pk_bf16(v[2], v[3]); w.z = cvt_pk_bf16(v[4], v[5]); w.w = cvt_pk_bf16(v[6], v[7]);
;                 *(u32x4*)rowp = w;
;             }
	v_mad_i64_i32 v[82:83], s[18:19], v82, s89, v[140:141]
	v_mul_f32_e32 v84, 0xbfb8aa3b, v78
	v_mul_f32_e32 v250, 0xbfb8aa3b, v79
	v_exp_f32_e32 v84, v84
	v_exp_f32_e32 v250, v250
	v_add_f32_e32 v84, 1.0, v84
	v_add_f32_e32 v250, 1.0, v250
	v_rcp_f32_e32 v84, v84
	v_rcp_f32_e32 v250, v250
	v_mul_f32_e32 v78, v78, v84
	v_mul_f32_e32 v250, v79, v250
	v_mul_f32_e32 v74, v78, v74
	v_mul_f32_e32 v75, v250, v75
	v_mul_f32_e32 v78, 0xbfb8aa3b, v80
	v_mul_f32_e32 v250, 0xbfb8aa3b, v81
	v_exp_f32_e32 v78, v78
	v_exp_f32_e32 v250, v250
	v_add_f32_e32 v78, 1.0, v78
	v_add_f32_e32 v250, 1.0, v250
	v_rcp_f32_e32 v78, v78
	v_rcp_f32_e32 v250, v250
	v_mul_f32_e32 v78, v80, v78
	v_mul_f32_e32 v250, v81, v250
	v_mul_f32_e32 v76, v78, v76
	v_mul_f32_e32 v77, v250, v77
	v_mul_f32_e32 v78, 0xbfb8aa3b, v70
	v_mul_f32_e32 v250, 0xbfb8aa3b, v71
	v_exp_f32_e32 v78, v78
	v_exp_f32_e32 v250, v250
	v_add_f32_e32 v78, 1.0, v78
	v_add_f32_e32 v250, 1.0, v250
	v_rcp_f32_e32 v78, v78
	v_rcp_f32_e32 v250, v250
	v_mul_f32_e32 v70, v70, v78
	v_mul_f32_e32 v250, v71, v250
	v_mul_f32_e32 v78, v70, v66
	v_mul_f32_e32 v79, v250, v67
	v_lshl_add_u64 v[70:71], v[82:83], 0, v[114:115]
	v_mul_f32_e32 v66, 0xbfb8aa3b, v72
	v_mul_f32_e32 v250, 0xbfb8aa3b, v73
	v_exp_f32_e32 v66, v66
	v_exp_f32_e32 v250, v250
	v_add_f32_e32 v66, 1.0, v66
	v_add_f32_e32 v250, 1.0, v250
	v_rcp_f32_e32 v66, v66
	v_rcp_f32_e32 v250, v250
	v_mul_f32_e32 v66, v72, v66
	v_mul_f32_e32 v250, v73, v250
	v_mul_f32_e32 v72, v66, v68
	v_mul_f32_e32 v69, v250, v69
	v_cvt_pk_bf16_f32 v66, v74, v75
	v_cvt_pk_bf16_f32 v67, v76, v77
	v_cvt_pk_bf16_f32 v68, v78, v79
	v_cvt_pk_bf16_f32 v69, v72, v69
	global_store_dwordx4 v[70:71], v[66:69], off
	s_nop 1
	v_add_u32_e32 v66, 0x80, v146
	v_mad_i64_i32 v[66:67], s[18:19], v66, s89, v[140:141]
	v_mul_f32_e32 v68, 0xbfb8aa3b, v62
	v_mul_f32_e32 v250, 0xbfb8aa3b, v63
	v_exp_f32_e32 v68, v68
	v_exp_f32_e32 v250, v250
	v_add_f32_e32 v68, 1.0, v68
	v_add_f32_e32 v250, 1.0, v250
	v_rcp_f32_e32 v68, v68
	v_rcp_f32_e32 v250, v250
	v_mul_f32_e32 v62, v62, v68
	v_mul_f32_e32 v250, v63, v250
	v_mul_f32_e32 v58, v62, v58
	v_mul_f32_e32 v59, v250, v59
	v_mul_f32_e32 v62, 0xbfb8aa3b, v64
	v_mul_f32_e32 v250, 0xbfb8aa3b, v65
	v_exp_f32_e32 v62, v62
	v_exp_f32_e32 v250, v250
	v_add_f32_e32 v62, 1.0, v62
	v_add_f32_e32 v250, 1.0, v250
	v_rcp_f32_e32 v62, v62
	v_rcp_f32_e32 v250, v250
	v_mul_f32_e32 v62, v64, v62
	v_mul_f32_e32 v250, v65, v250
	v_mul_f32_e32 v60, v62, v60
	v_mul_f32_e32 v61, v250, v61
	v_mul_f32_e32 v62, 0xbfb8aa3b, v54
	v_mul_f32_e32 v250, 0xbfb8aa3b, v55
	v_exp_f32_e32 v62, v62
	v_exp_f32_e32 v250, v250
	v_add_f32_e32 v62, 1.0, v62
	v_add_f32_e32 v250, 1.0, v250
	v_rcp_f32_e32 v62, v62
	v_rcp_f32_e32 v250, v250
	v_mul_f32_e32 v54, v54, v62
	v_mul_f32_e32 v250, v55, v250
	v_mul_f32_e32 v62, v54, v50
	v_mul_f32_e32 v63, v250, v51
	v_lshl_add_u64 v[54:55], v[66:67], 0, v[114:115]
	v_mul_f32_e32 v50, 0xbfb8aa3b, v56
	v_mul_f32_e32 v250, 0xbfb8aa3b, v57
	v_exp_f32_e32 v50, v50
	v_exp_f32_e32 v250, v250
	v_add_f32_e32 v50, 1.0, v50
	v_add_f32_e32 v250, 1.0, v250
	v_rcp_f32_e32 v50, v50
	v_rcp_f32_e32 v250, v250
	v_mul_f32_e32 v50, v56, v50
	v_mul_f32_e32 v250, v57, v250
	v_mul_f32_e32 v56, v50, v52
	v_mul_f32_e32 v53, v250, v53
	v_cvt_pk_bf16_f32 v50, v58, v59
	v_cvt_pk_bf16_f32 v51, v60, v61
	v_cvt_pk_bf16_f32 v52, v62, v63
	v_cvt_pk_bf16_f32 v53, v56, v53
	global_store_dwordx4 v[54:55], v[50:53], off
	s_nop 1
	v_add_u32_e32 v50, 0x90, v146
	v_mad_i64_i32 v[50:51], s[18:19], v50, s89, v[140:141]
	v_mul_f32_e32 v52, 0xbfb8aa3b, v46
	v_mul_f32_e32 v250, 0xbfb8aa3b, v47
	v_exp_f32_e32 v52, v52
	v_exp_f32_e32 v250, v250
	v_add_f32_e32 v52, 1.0, v52
	v_add_f32_e32 v250, 1.0, v250
	v_rcp_f32_e32 v52, v52
	v_rcp_f32_e32 v250, v250
	v_mul_f32_e32 v46, v46, v52
	v_mul_f32_e32 v250, v47, v250
	v_mul_f32_e32 v42, v46, v42
	v_mul_f32_e32 v43, v250, v43
	v_mul_f32_e32 v46, 0xbfb8aa3b, v48
	v_mul_f32_e32 v250, 0xbfb8aa3b, v49
	v_exp_f32_e32 v46, v46
	v_exp_f32_e32 v250, v250
	v_add_f32_e32 v46, 1.0, v46
	v_add_f32_e32 v250, 1.0, v250
	v_rcp_f32_e32 v46, v46
	v_rcp_f32_e32 v250, v250
	v_mul_f32_e32 v46, v48, v46
	v_mul_f32_e32 v250, v49, v250
	v_mul_f32_e32 v44, v46, v44
	v_mul_f32_e32 v45, v250, v45
	v_mul_f32_e32 v46, 0xbfb8aa3b, v38
	v_mul_f32_e32 v250, 0xbfb8aa3b, v39
	v_exp_f32_e32 v46, v46
	v_exp_f32_e32 v250, v250
; __device__ __forceinline__ unsigned cvt_pk_bf16(float lo, float hi) { unsigned r; asm volatile("v_cvt_pk_bf16_f32 %0, %1, %2" : "=v"(r) : "v"(lo), "v"(hi)); return r; }
; __device__ __forceinline__ float sigmoid_f(float x) { return __builtin_amdgcn_rcpf(1.0f + __builtin_amdgcn_exp2f(-1.4426950408889634f * x)); }
; #define PG8_BAR __builtin_amdgcn_s_barrier()
;     __device__ __forceinline__ void operator()(const f32x4 (&acc)[2][2][4][2], const Unit& u, int wr, int wc, int fr, int fq) const {
;         const int row0 = u.pm * BM + wr * 64 + fr, col0 = u.pn * HALF + wc * 32 + 8 * fq;
; #pragma unroll
;         for (int ai = 0; ai < 2; ++ai)
; #pragma unroll
;             for (int m = 0; m < 4; ++m) {
;                 bf16_t* rowp = O + (size_t)(row0 + ai * HALF + m * 16) * ldc + col0;
;                 float v[8];
; #pragma unroll
;                 for (int n = 0; n < 2; ++n)
; #pragma unroll
;                     for (int e = 0; e < 4; ++e) { const float g = acc[ai][0][m][n][e], up = acc[ai][1][m][n][e]; v[4 * n + e] = g * sigmoid_f(g) * up; }
;                 u32x4 w; w.x = cvt_pk_bf16(v[0], v[1]); w.y = cvt_pk_bf16(v[2], v[3]); w.z = cvt_pk_bf16(v[4], v[5]); w.w = cvt_pk_bf16(v[6], v[7]);
;                 *(u32x4*)rowp = w;
;             }
; template <class Epi, class Sched, bool ALIGN_EPI = false, bool SP2 = false>
; __device__ __forceinline__ void gemm_phase(PG8_LAS unsigned char* lds, const Gemm g, const Sched& S, const Epi& E) {
;     ...
;         if constexpr (ALIGN_EPI) { if (wr == 0) PG8_BAR; }
;         if constexpr (!Epi::AFTER_DRAIN) { E(acc, cur, wr, wc, fr, fq); S.done(cur); }
;         if (!has_next) break;
; #pragma unroll
;         for (int a = 0; a < 2; ++a)
; #pragma unroll
;             for (int b = 0; b < 2; ++b)
; #pragma unroll
;                 for (int m = 0; m < 4; ++m)
; #pragma unroll
;                     for (int n = 0; n < 2; ++n) acc[a][b][m][n] = (f32x4){0.f, 0.f, 0.f, 0.f};
;         cur = nxt; cA = nA; cB = nB; ++ui;
;         if constexpr (ALIGN_EPI) { if (wr == 1) PG8_BAR; }
	v_add_f32_e32 v46, 1.0, v46
	v_add_f32_e32 v250, 1.0, v250
	v_rcp_f32_e32 v46, v46
	v_rcp_f32_e32 v250, v250
	v_mul_f32_e32 v38, v38, v46
	v_mul_f32_e32 v250, v39, v250
	v_mul_f32_e32 v46, v38, v34
	v_mul_f32_e32 v47, v250, v35
	v_lshl_add_u64 v[38:39], v[50:51], 0, v[114:115]
	v_mul_f32_e32 v34, 0xbfb8aa3b, v40
	v_mul_f32_e32 v250, 0xbfb8aa3b, v41
	v_exp_f32_e32 v34, v34
	v_exp_f32_e32 v250, v250
	v_add_f32_e32 v34, 1.0, v34
	v_add_f32_e32 v250, 1.0, v250
	v_rcp_f32_e32 v34, v34
	v_rcp_f32_e32 v250, v250
	v_mul_f32_e32 v34, v40, v34
	v_mul_f32_e32 v250, v41, v250
	v_mul_f32_e32 v40, v34, v36
	v_mul_f32_e32 v37, v250, v37
	v_cvt_pk_bf16_f32 v34, v42, v43
	v_cvt_pk_bf16_f32 v35, v44, v45
	v_cvt_pk_bf16_f32 v36, v46, v47
	v_cvt_pk_bf16_f32 v37, v40, v37
	global_store_dwordx4 v[38:39], v[34:37], off
	s_nop 1
	v_add_u32_e32 v34, 0xa0, v146
	v_mad_i64_i32 v[34:35], s[18:19], v34, s89, v[140:141]
	v_mul_f32_e32 v36, 0xbfb8aa3b, v30
	v_mul_f32_e32 v250, 0xbfb8aa3b, v31
	v_exp_f32_e32 v36, v36
	v_exp_f32_e32 v250, v250
	v_add_f32_e32 v36, 1.0, v36
	v_add_f32_e32 v250, 1.0, v250
	v_rcp_f32_e32 v36, v36
	v_rcp_f32_e32 v250, v250
	v_mul_f32_e32 v30, v30, v36
	v_mul_f32_e32 v250, v31, v250
	v_mul_f32_e32 v26, v30, v26
	v_mul_f32_e32 v27, v250, v27
	v_mul_f32_e32 v30, 0xbfb8aa3b, v32
	v_mul_f32_e32 v250, 0xbfb8aa3b, v33
	v_exp_f32_e32 v30, v30
	v_exp_f32_e32 v250, v250
	v_add_f32_e32 v30, 1.0, v30
	v_add_f32_e32 v250, 1.0, v250
	v_rcp_f32_e32 v30, v30
	v_rcp_f32_e32 v250, v250
	v_mul_f32_e32 v30, v32, v30
	v_mul_f32_e32 v250, v33, v250
	v_mul_f32_e32 v28, v30, v28
	v_mul_f32_e32 v29, v250, v29
	v_mul_f32_e32 v30, 0xbfb8aa3b, v22
	v_mul_f32_e32 v250, 0xbfb8aa3b, v23
	v_exp_f32_e32 v30, v30
	v_exp_f32_e32 v250, v250
	v_add_f32_e32 v30, 1.0, v30
	v_add_f32_e32 v250, 1.0, v250
	v_rcp_f32_e32 v30, v30
	v_rcp_f32_e32 v250, v250
	v_mul_f32_e32 v22, v22, v30
	v_mul_f32_e32 v250, v23, v250
	v_mul_f32_e32 v30, v22, v18
	v_mul_f32_e32 v31, v250, v19
	v_lshl_add_u64 v[22:23], v[34:35], 0, v[114:115]
	v_mul_f32_e32 v18, 0xbfb8aa3b, v24
	v_mul_f32_e32 v250, 0xbfb8aa3b, v25
	v_exp_f32_e32 v18, v18
	v_exp_f32_e32 v250, v250
	v_add_f32_e32 v18, 1.0, v18
	v_add_f32_e32 v250, 1.0, v250
	v_rcp_f32_e32 v18, v18
	v_rcp_f32_e32 v250, v250
	v_mul_f32_e32 v18, v24, v18
	v_mul_f32_e32 v250, v25, v250
	v_mul_f32_e32 v24, v18, v20
	v_mul_f32_e32 v21, v250, v21
	v_cvt_pk_bf16_f32 v18, v26, v27
	v_cvt_pk_bf16_f32 v19, v28, v29
	v_cvt_pk_bf16_f32 v20, v30, v31
	v_cvt_pk_bf16_f32 v21, v24, v21
	global_store_dwordx4 v[22:23], v[18:21], off
	s_nop 1
	v_add_u32_e32 v18, 0xb0, v146
	v_mad_i64_i32 v[18:19], s[18:19], v18, s89, v[140:141]
	v_mul_f32_e32 v20, 0xbfb8aa3b, v14
	v_mul_f32_e32 v250, 0xbfb8aa3b, v15
	v_exp_f32_e32 v20, v20
	v_exp_f32_e32 v250, v250
	v_add_f32_e32 v20, 1.0, v20
	v_add_f32_e32 v250, 1.0, v250
	v_rcp_f32_e32 v20, v20
	v_rcp_f32_e32 v250, v250
	v_mul_f32_e32 v14, v14, v20
	v_mul_f32_e32 v250, v15, v250
	v_mul_f32_e32 v10, v14, v10
	v_mul_f32_e32 v11, v250, v11
	v_mul_f32_e32 v14, 0xbfb8aa3b, v16
	v_mul_f32_e32 v250, 0xbfb8aa3b, v17
	v_exp_f32_e32 v14, v14
	v_exp_f32_e32 v250, v250
	v_add_f32_e32 v14, 1.0, v14
	v_add_f32_e32 v250, 1.0, v250
	v_rcp_f32_e32 v14, v14
	v_rcp_f32_e32 v250, v250
	v_mul_f32_e32 v14, v16, v14
	v_mul_f32_e32 v250, v17, v250
	v_mul_f32_e32 v12, v14, v12
	v_mul_f32_e32 v13, v250, v13
	v_mul_f32_e32 v14, 0xbfb8aa3b, v6
	v_mul_f32_e32 v250, 0xbfb8aa3b, v7
	v_exp_f32_e32 v14, v14
	v_exp_f32_e32 v250, v250
	v_add_f32_e32 v14, 1.0, v14
	v_add_f32_e32 v250, 1.0, v250
	v_rcp_f32_e32 v14, v14
	v_rcp_f32_e32 v250, v250
	v_mul_f32_e32 v6, v6, v14
	v_mul_f32_e32 v250, v7, v250
	v_mul_f32_e32 v14, v6, v2
	v_mul_f32_e32 v15, v250, v3
	v_lshl_add_u64 v[6:7], v[18:19], 0, v[114:115]
	v_mul_f32_e32 v2, 0xbfb8aa3b, v8
	v_mul_f32_e32 v250, 0xbfb8aa3b, v9
	v_exp_f32_e32 v2, v2
	v_exp_f32_e32 v250, v250
	v_add_f32_e32 v2, 1.0, v2
	v_add_f32_e32 v250, 1.0, v250
	v_rcp_f32_e32 v2, v2
	v_rcp_f32_e32 v250, v250
	v_mul_f32_e32 v2, v8, v2
	v_mul_f32_e32 v250, v9, v250
	v_mul_f32_e32 v8, v2, v4
	v_mul_f32_e32 v5, v250, v5
	v_cvt_pk_bf16_f32 v2, v10, v11
	v_cvt_pk_bf16_f32 v3, v12, v13
	v_cvt_pk_bf16_f32 v4, v14, v15
	v_cvt_pk_bf16_f32 v5, v8, v5
	global_store_dwordx4 v[6:7], v[2:5], off
	s_cbranch_vccnz .LBB0_504
	s_andn2_b64 vcc, exec, s[8:9]
	s_cbranch_vccnz .LBB0_503
	s_barrier
	s_branch .LBB0_503
